# differential loop role B: staging stores one phase earlier (after the first half of its PV MFMAs)
# baseline (speedup 1.0000x reference)
; template <bool DIFF>
; __device__ __forceinline__ void attn_unit(const AttnP& A, int b, int h, int qi, ldsp lds) {
;     ...
;             QK_BLOCK();
;             s16x4 vlo[8], vhi[8];
; #pragma unroll
;             for (int t = 0; t < 2; ++t)
; #pragma unroll
;                 for (int j = 0; j < 4; ++j) { vlo[t * 4 + j] = vtr(Vb + trb + (16 * j) * VP + t * 64); vhi[t * 4 + j] = vtr(Vb + trb + (16 * j + 8) * VP + t * 64); }
;             __builtin_amdgcn_sched_barrier(0);
;             MASK_BLOCK();
;             bool full = (kt == kt0);
;             float psa, psb;
;             if (!full) {
;                 EXPSUM_BLOCK();
;                 if (__any(psa + psb > 1.0e18f)) { full = true; QK_BLOCK();
;     ...
;             bf16x8 pw[4];
; #pragma unroll
;             for (int j = 0; j < 4; ++j) {
;                 u32x4 pk;
;                 if (j < 2) { const int rb = 8 * (j & 1); pk.x = cvtpk(s0[rb], s0[rb + 1]); pk.y = cvtpk(s0[rb + 2], s0[rb + 3]); pk.z = cvtpk(s0[rb + 4], s0[rb + 5]); pk.w = cvtpk(s0[rb + 6], s0[rb + 7]); }
;                 else { const int rb = 8 * (j & 1); pk.x = cvtpk(s1[rb], s1[rb + 1]); pk.y = cvtpk(s1[rb + 2], s1[rb + 3]); pk.z = cvtpk(s1[rb + 4], s1[rb + 5]); pk.w = cvtpk(s1[rb + 6], s1[rb + 7]); }
;                 pw[j] = __builtin_bit_cast(bf16x8, pk);
;             }
;             __builtin_amdgcn_sched_barrier(0);
;             __builtin_amdgcn_s_setprio(1);
; #pragma unroll
;             for (int t = 0; t < 2; ++t)
; #pragma unroll
;                 for (int j = 0; j < 4; ++j) {
;                     const bf16x8 vf = (bf16x8){vlo[t * 4 + j][0], vlo[t * 4 + j][1], vlo[t * 4 + j][2], vlo[t * 4 + j][3], vhi[t * 4 + j][0], vhi[t * 4 + j][1], vhi[t * 4 + j][2], vhi[t * 4 + j][3]};
;                     o[t] = __builtin_amdgcn_mfma_f32_32x32x16_bf16(vf, pw[j], o[t], 0, 0, 0);
;                 }
;             if (DIFF) {
; #pragma unroll
;                 for (int t = 2; t < NTD; ++t)
; #pragma unroll
;                     for (int j = 0; j < 4; ++j) { vlo[(t - 2) * 4 + j] = vtr(Vb + trb + (16 * j) * VP + t * 64); vhi[(t - 2) * 4 + j] = vtr(Vb + trb + (16 * j + 8) * VP + t * 64); }
;                 __builtin_amdgcn_sched_barrier(0);
; #pragma unroll
;                 for (int t = 2; t < NTD; ++t)
; #pragma unroll
;                     for (int j = 0; j < 4; ++j) {
;                         const int i = (t - 2) * 4 + j;
.Ldb_s_even:
	v_exp_f32_e32 v148, v98
	v_exp_f32_e32 v164, v82
	v_exp_f32_e32 v149, v99
	v_exp_f32_e32 v165, v83
	v_add_f32_e32 v237, 0, v148
	v_add_f32_e32 v238, 0, v164
	v_exp_f32_e32 v150, v100
	v_exp_f32_e32 v166, v84
	v_add_f32_e32 v237, v149, v237
	v_add_f32_e32 v238, v165, v238
	v_exp_f32_e32 v151, v101
	v_exp_f32_e32 v167, v85
	v_add_f32_e32 v237, v150, v237
	v_add_f32_e32 v238, v166, v238
	v_exp_f32_e32 v152, v102
	v_exp_f32_e32 v168, v86
	v_add_f32_e32 v237, v151, v237
	v_add_f32_e32 v238, v167, v238
	v_exp_f32_e32 v153, v103
	v_exp_f32_e32 v169, v87
	v_add_f32_e32 v237, v152, v237
	v_add_f32_e32 v238, v168, v238
	v_exp_f32_e32 v154, v104
	v_exp_f32_e32 v170, v88
	v_add_f32_e32 v237, v153, v237
	v_add_f32_e32 v238, v169, v238
	v_exp_f32_e32 v155, v105
	v_exp_f32_e32 v171, v89
	v_add_f32_e32 v237, v154, v237
	v_add_f32_e32 v238, v170, v238
	v_exp_f32_e32 v156, v106
	v_exp_f32_e32 v172, v90
	v_add_f32_e32 v237, v155, v237
	v_add_f32_e32 v238, v171, v238
	v_exp_f32_e32 v157, v107
	v_exp_f32_e32 v173, v91
	v_add_f32_e32 v237, v156, v237
	v_add_f32_e32 v238, v172, v238
	v_exp_f32_e32 v158, v108
	v_exp_f32_e32 v174, v92
	v_add_f32_e32 v237, v157, v237
	v_add_f32_e32 v238, v173, v238
	v_exp_f32_e32 v159, v109
	v_exp_f32_e32 v175, v93
	v_add_f32_e32 v237, v158, v237
	v_add_f32_e32 v238, v174, v238
	v_exp_f32_e32 v160, v110
	v_exp_f32_e32 v176, v94
	v_add_f32_e32 v237, v159, v237
	v_add_f32_e32 v238, v175, v238
	v_exp_f32_e32 v161, v111
	v_exp_f32_e32 v177, v95
	v_add_f32_e32 v237, v160, v237
	v_add_f32_e32 v238, v176, v238
	v_exp_f32_e32 v162, v112
	v_exp_f32_e32 v178, v96
	v_add_f32_e32 v237, v161, v237
	v_add_f32_e32 v238, v177, v238
	v_exp_f32_e32 v163, v113
	v_exp_f32_e32 v179, v97
	v_add_f32_e32 v237, v162, v237
	v_add_f32_e32 v238, v178, v238
	s_nop 0
	v_add_f32_e32 v237, v163, v237
	v_add_f32_e32 v238, v179, v238
	v_add_f32_e32 v204, v237, v238
	v_cmp_lt_f32_e32 vcc, s85, v204
	s_cbranch_vccnz .Ldb_s_slow
	ds_read_b64_tr_b16 v[90:91], v252 offset:17472
	ds_read_b64_tr_b16 v[92:93], v252 offset:20032
	ds_read_b64_tr_b16 v[94:95], v252 offset:17408
	ds_read_b64_tr_b16 v[96:97], v252 offset:19968
	ds_read_b64_tr_b16 v[106:107], v252 offset:22592
	ds_read_b64_tr_b16 v[108:109], v252 offset:25152
	ds_read_b64_tr_b16 v[110:111], v252 offset:22528
	ds_read_b64_tr_b16 v[112:113], v252 offset:25088
	ds_read_b64_tr_b16 v[240:241], v252 offset:27712
	ds_read_b64_tr_b16 v[242:243], v252 offset:30272
	v_cvt_pk_bf16_f32 v98, v148, v149
	v_cvt_pk_bf16_f32 v99, v150, v151
	v_cvt_pk_bf16_f32 v100, v152, v153
	v_cvt_pk_bf16_f32 v101, v154, v155
	v_cvt_pk_bf16_f32 v102, v156, v157
	v_cvt_pk_bf16_f32 v103, v158, v159
	v_cvt_pk_bf16_f32 v104, v160, v161
	v_cvt_pk_bf16_f32 v105, v162, v163
	v_cvt_pk_bf16_f32 v82, v164, v165
	v_cvt_pk_bf16_f32 v83, v166, v167
	v_cvt_pk_bf16_f32 v84, v168, v169
	v_cvt_pk_bf16_f32 v85, v170, v171
	v_cvt_pk_bf16_f32 v86, v172, v173
	v_cvt_pk_bf16_f32 v87, v174, v175
	v_cvt_pk_bf16_f32 v88, v176, v177
	v_cvt_pk_bf16_f32 v89, v178, v179
	v_add_f32_e32 v230, v204, v230
	ds_read_b64_tr_b16 v[148:149], v252 offset:27648
	ds_read_b64_tr_b16 v[150:151], v252 offset:30208
	ds_read_b64_tr_b16 v[152:153], v252 offset:32768
	ds_read_b64_tr_b16 v[154:155], v252 offset:35328
	ds_read_b64_tr_b16 v[156:157], v252 offset:32832
	ds_read_b64_tr_b16 v[158:159], v252 offset:35392
	s_setprio 1
	s_waitcnt lgkmcnt(14)
	v_mfma_f32_32x32x16_bf16 v[34:49], v[90:93], v[98:101], v[34:49]
	ds_read_b64_tr_b16 v[160:161], v252 offset:17536
	ds_read_b64_tr_b16 v[162:163], v252 offset:20096
	s_waitcnt lgkmcnt(14)
	v_mfma_f32_32x32x16_bf16 v[50:65], v[94:97], v[98:101], v[50:65]
	ds_read_b64_tr_b16 v[164:165], v252 offset:17600
	ds_read_b64_tr_b16 v[166:167], v252 offset:20160
	s_waitcnt lgkmcnt(14)
	v_mfma_f32_32x32x16_bf16 v[34:49], v[106:109], v[102:105], v[34:49]
	ds_read_b64_tr_b16 v[168:169], v252 offset:22656
	ds_read_b64_tr_b16 v[170:171], v252 offset:25216
	s_waitcnt lgkmcnt(14)
	v_mfma_f32_32x32x16_bf16 v[50:65], v[110:113], v[102:105], v[50:65]
	ds_read_b64_tr_b16 v[172:173], v252 offset:22720
	ds_read_b64_tr_b16 v[174:175], v252 offset:25280
	s_waitcnt lgkmcnt(14)
	v_mfma_f32_32x32x16_bf16 v[34:49], v[240:243], v[82:85], v[34:49]
	ds_read_b64_tr_b16 v[176:177], v252 offset:27776
	ds_read_b64_tr_b16 v[178:179], v252 offset:30336
	s_waitcnt lgkmcnt(14)
	v_mfma_f32_32x32x16_bf16 v[50:65], v[148:151], v[82:85], v[50:65]
	ds_read_b64_tr_b16 v[90:91], v252 offset:27840
	ds_read_b64_tr_b16 v[92:93], v252 offset:30400
	s_waitcnt lgkmcnt(14)
	v_mfma_f32_32x32x16_bf16 v[50:65], v[152:155], v[86:89], v[50:65]
	ds_read_b64_tr_b16 v[94:95], v252 offset:32896
	ds_read_b64_tr_b16 v[96:97], v252 offset:35456
	s_waitcnt lgkmcnt(14)
	v_mfma_f32_32x32x16_bf16 v[34:49], v[156:159], v[86:89], v[34:49]
	ds_read_b64_tr_b16 v[106:107], v252 offset:32960
	ds_read_b64_tr_b16 v[108:109], v252 offset:35520
	s_waitcnt vmcnt(0)
	ds_write_b128 v226, v[132:135] offset:38144
	ds_write_b128 v228, v[140:143] offset:38144
	ds_write_b128 v227, v[136:139] offset:17408
	ds_write_b128 v229, v[144:147] offset:17408
	global_load_dwordx4 v[136:139], v[196:197], off offset:2048
	global_load_dwordx4 v[144:147], v[198:199], off offset:2048
	v_lshl_add_u64 v[196:197], v[196:197], 0, s[26:27]
	v_lshl_add_u64 v[198:199], v[198:199], 0, s[26:27]
	global_load_dwordx4 v[132:135], v[196:197], off offset:1024
	global_load_dwordx4 v[140:143], v[198:199], off offset:1024
	s_waitcnt lgkmcnt(15)
	v_mfma_f32_32x32x16_bf16 v[18:33], v[160:163], v[98:101], v[18:33]
	ds_read_b128 v[240:243], v234
	s_waitcnt lgkmcnt(15)
	v_mfma_f32_32x32x16_bf16 v[2:17], v[164:167], v[98:101], v[2:17]
	ds_read_b128 v[148:151], v234 offset:8704
	s_waitcnt lgkmcnt(15)
; __device__ __forceinline__ s16x4 vtr(ldsp p) { return __builtin_bit_cast(s16x4, __builtin_amdgcn_ds_read_tr16_b64_v4i16((LAS v4i16_t*)p)); }
; #define MASK_BLOCK() do { if (kt == 0 || kt >= diag0) { \
;             _Pragma("unroll") for (int r = 0; r < 16; ++r) { const int kpp = 64 * kt + crow(r, hi); \
;                 if (kpp < 48 || kpp > q_pp) s0[r] = -INFINITY; \
;                 if (kpp + 32 < 48 || kpp + 32 > q_pp) s1[r] = -INFINITY; } } } while (0)
; #define EXPSUM_BLOCK() do { psa = 0.f; psb = 0.f; \
;             _Pragma("unroll") for (int r = 0; r < 16; ++r) { s0[r] = __builtin_amdgcn_exp2f(s0[r]); s1[r] = __builtin_amdgcn_exp2f(s1[r]); psa += s0[r]; asm("" : "+v"(psa)); psb += s1[r]; asm("" : "+v"(psb)); } } while (0)
; template <bool DIFF>
; __device__ __forceinline__ void attn_unit(const AttnP& A, int b, int h, int qi, ldsp lds) {
;     ...
;             QK_BLOCK();
;             s16x4 vlo[8], vhi[8];
; #pragma unroll
;             for (int t = 0; t < 2; ++t)
; #pragma unroll
;                 for (int j = 0; j < 4; ++j) { vlo[t * 4 + j] = vtr(Vb + trb + (16 * j) * VP + t * 64); vhi[t * 4 + j] = vtr(Vb + trb + (16 * j + 8) * VP + t * 64); }
;             __builtin_amdgcn_sched_barrier(0);
;             MASK_BLOCK();
;             bool full = (kt == kt0);
;             float psa, psb;
;             if (!full) {
;                 EXPSUM_BLOCK();
;                 if (__any(psa + psb > 1.0e18f)) { full = true; QK_BLOCK();
	v_mfma_f32_32x32x16_bf16 v[18:33], v[168:171], v[102:105], v[18:33]
	ds_read_b128 v[152:155], v234 offset:32
	s_waitcnt lgkmcnt(15)
	v_mfma_f32_32x32x16_bf16 v[2:17], v[172:175], v[102:105], v[2:17]
	ds_read_b128 v[156:159], v234 offset:8736
	s_waitcnt lgkmcnt(14)
	v_mfma_f32_32x32x16_bf16 v[18:33], v[176:179], v[82:85], v[18:33]
	ds_read_b128 v[160:163], v234 offset:64
	s_waitcnt lgkmcnt(13)
	v_mfma_f32_32x32x16_bf16 v[2:17], v[90:93], v[82:85], v[2:17]
	ds_read_b128 v[164:167], v234 offset:8768
	s_waitcnt lgkmcnt(12)
	v_mfma_f32_32x32x16_bf16 v[18:33], v[94:97], v[86:89], v[18:33]
	ds_read_b128 v[168:171], v234 offset:96
	s_waitcnt lgkmcnt(11)
	v_mfma_f32_32x32x16_bf16 v[2:17], v[106:109], v[86:89], v[2:17]
	ds_read_b128 v[172:175], v234 offset:8800
	s_waitcnt lgkmcnt(7)
	v_mfma_f32_32x32x16_bf16 v[98:113], v[240:243], v[116:119], v[66:81]
	s_waitcnt lgkmcnt(6)
	v_mfma_f32_32x32x16_bf16 v[82:97], v[148:151], v[116:119], v[66:81]
	s_waitcnt lgkmcnt(5)
	v_mfma_f32_32x32x16_bf16 v[98:113], v[152:155], v[120:123], v[98:113]
	s_waitcnt lgkmcnt(4)
	v_mfma_f32_32x32x16_bf16 v[82:97], v[156:159], v[120:123], v[82:97]
	s_waitcnt lgkmcnt(3)
	v_mfma_f32_32x32x16_bf16 v[98:113], v[160:163], v[124:127], v[98:113]
	s_waitcnt lgkmcnt(2)
	v_mfma_f32_32x32x16_bf16 v[82:97], v[164:167], v[124:127], v[82:97]
	s_waitcnt lgkmcnt(1)
	v_mfma_f32_32x32x16_bf16 v[98:113], v[168:171], v[128:131], v[98:113]
	s_waitcnt lgkmcnt(0)
	v_mfma_f32_32x32x16_bf16 v[82:97], v[172:175], v[128:131], v[82:97]
	s_setprio 0
	s_waitcnt lgkmcnt(0)
	s_barrier
	s_add_i32 s75, s75, 1
	s_add_i32 s74, s74, 64
	s_cmp_gt_i32 s75, s23
	s_cbranch_scc1 .Ldb_gen
.Ldb_s_odd:
	v_exp_f32_e32 v148, v98
	v_exp_f32_e32 v164, v82
	v_exp_f32_e32 v149, v99
	v_exp_f32_e32 v165, v83
	v_add_f32_e32 v237, 0, v148
	v_add_f32_e32 v238, 0, v164
	v_exp_f32_e32 v150, v100
	v_exp_f32_e32 v166, v84
	v_add_f32_e32 v237, v149, v237
	v_add_f32_e32 v238, v165, v238
	v_exp_f32_e32 v151, v101
	v_exp_f32_e32 v167, v85
	v_add_f32_e32 v237, v150, v237
	v_add_f32_e32 v238, v166, v238
	v_exp_f32_e32 v152, v102
	v_exp_f32_e32 v168, v86
	v_add_f32_e32 v237, v151, v237
	v_add_f32_e32 v238, v167, v238
	v_exp_f32_e32 v153, v103
	v_exp_f32_e32 v169, v87
	v_add_f32_e32 v237, v152, v237
	v_add_f32_e32 v238, v168, v238
	v_exp_f32_e32 v154, v104
	v_exp_f32_e32 v170, v88
	v_add_f32_e32 v237, v153, v237
	v_add_f32_e32 v238, v169, v238
	v_exp_f32_e32 v155, v105
	v_exp_f32_e32 v171, v89
	v_add_f32_e32 v237, v154, v237
	v_add_f32_e32 v238, v170, v238
	v_exp_f32_e32 v156, v106
	v_exp_f32_e32 v172, v90
	v_add_f32_e32 v237, v155, v237
	v_add_f32_e32 v238, v171, v238
	v_exp_f32_e32 v157, v107
	v_exp_f32_e32 v173, v91
	v_add_f32_e32 v237, v156, v237
	v_add_f32_e32 v238, v172, v238
	v_exp_f32_e32 v158, v108
	v_exp_f32_e32 v174, v92
	v_add_f32_e32 v237, v157, v237
	v_add_f32_e32 v238, v173, v238
	v_exp_f32_e32 v159, v109
	v_exp_f32_e32 v175, v93
	v_add_f32_e32 v237, v158, v237
	v_add_f32_e32 v238, v174, v238
	v_exp_f32_e32 v160, v110
	v_exp_f32_e32 v176, v94
	v_add_f32_e32 v237, v159, v237
	v_add_f32_e32 v238, v175, v238
	v_exp_f32_e32 v161, v111
	v_exp_f32_e32 v177, v95
	v_add_f32_e32 v237, v160, v237
	v_add_f32_e32 v238, v176, v238
	v_exp_f32_e32 v162, v112
	v_exp_f32_e32 v178, v96
	v_add_f32_e32 v237, v161, v237
	v_add_f32_e32 v238, v177, v238
	v_exp_f32_e32 v163, v113
	v_exp_f32_e32 v179, v97
	v_add_f32_e32 v237, v162, v237
	v_add_f32_e32 v238, v178, v238
	s_nop 0
	v_add_f32_e32 v237, v163, v237
	v_add_f32_e32 v238, v179, v238
	v_add_f32_e32 v204, v237, v238
	v_cmp_lt_f32_e32 vcc, s85, v204
	s_cbranch_vccnz .Ldb_s_slow
; __device__ __forceinline__ unsigned cvtpk(float lo, float hi) { f32x2 v = {lo, hi}; bf16x2_t b = __builtin_convertvector(v, bf16x2_t); return __builtin_bit_cast(unsigned, b); }
; template <bool DIFF>
; __device__ __forceinline__ void attn_unit(const AttnP& A, int b, int h, int qi, ldsp lds) {
;     ...
;             bf16x8 pw[4];
; #pragma unroll
;             for (int j = 0; j < 4; ++j) {
;                 u32x4 pk;
;                 if (j < 2) { const int rb = 8 * (j & 1); pk.x = cvtpk(s0[rb], s0[rb + 1]); pk.y = cvtpk(s0[rb + 2], s0[rb + 3]); pk.z = cvtpk(s0[rb + 4], s0[rb + 5]); pk.w = cvtpk(s0[rb + 6], s0[rb + 7]); }
;                 else { const int rb = 8 * (j & 1); pk.x = cvtpk(s1[rb], s1[rb + 1]); pk.y = cvtpk(s1[rb + 2], s1[rb + 3]); pk.z = cvtpk(s1[rb + 4], s1[rb + 5]); pk.w = cvtpk(s1[rb + 6], s1[rb + 7]); }
;                 pw[j] = __builtin_bit_cast(bf16x8, pk);
;             }
;             __builtin_amdgcn_sched_barrier(0);
;             __builtin_amdgcn_s_setprio(1);
; #pragma unroll
;             for (int t = 0; t < 2; ++t)
; #pragma unroll
;                 for (int j = 0; j < 4; ++j) {
;                     const bf16x8 vf = (bf16x8){vlo[t * 4 + j][0], vlo[t * 4 + j][1], vlo[t * 4 + j][2], vlo[t * 4 + j][3], vhi[t * 4 + j][0], vhi[t * 4 + j][1], vhi[t * 4 + j][2], vhi[t * 4 + j][3]};
;                     o[t] = __builtin_amdgcn_mfma_f32_32x32x16_bf16(vf, pw[j], o[t], 0, 0, 0);
;                 }
;             if (DIFF) {
; #pragma unroll
;                 for (int t = 2; t < NTD; ++t)
; #pragma unroll
;                     for (int j = 0; j < 4; ++j) { vlo[(t - 2) * 4 + j] = vtr(Vb + trb + (16 * j) * VP + t * 64); vhi[(t - 2) * 4 + j] = vtr(Vb + trb + (16 * j + 8) * VP + t * 64); }
;                 __builtin_amdgcn_sched_barrier(0);
; #pragma unroll
;                 for (int t = 2; t < NTD; ++t)
; #pragma unroll
;                     for (int j = 0; j < 4; ++j) {
;                         const int i = (t - 2) * 4 + j;
;                         const bf16x8 vf = (bf16x8){vlo[i][0], vlo[i][1], vlo[i][2], vlo[i][3], vhi[i][0], vhi[i][1], vhi[i][2], vhi[i][3]};
;                         o[t] = __builtin_amdgcn_mfma_f32_32x32x16_bf16(vf, pw[j], o[t], 0, 0, 0);
;                     }
;             }
;             __builtin_amdgcn_s_setprio(0);
;         }
;         if (kt + 1 < nt) STORE_TILE((kt + 1) & 1);
;         __syncthreads();
;     }
	ds_read_b64_tr_b16 v[90:91], v231 offset:17472
	ds_read_b64_tr_b16 v[92:93], v231 offset:20032
	ds_read_b64_tr_b16 v[94:95], v231 offset:17408
	ds_read_b64_tr_b16 v[96:97], v231 offset:19968
	ds_read_b64_tr_b16 v[106:107], v231 offset:22592
	ds_read_b64_tr_b16 v[108:109], v231 offset:25152
	ds_read_b64_tr_b16 v[110:111], v231 offset:22528
	ds_read_b64_tr_b16 v[112:113], v231 offset:25088
	ds_read_b64_tr_b16 v[240:241], v231 offset:27712
	ds_read_b64_tr_b16 v[242:243], v231 offset:30272
	v_cvt_pk_bf16_f32 v98, v148, v149
	v_cvt_pk_bf16_f32 v99, v150, v151
	v_cvt_pk_bf16_f32 v100, v152, v153
	v_cvt_pk_bf16_f32 v101, v154, v155
	v_cvt_pk_bf16_f32 v102, v156, v157
	v_cvt_pk_bf16_f32 v103, v158, v159
	v_cvt_pk_bf16_f32 v104, v160, v161
	v_cvt_pk_bf16_f32 v105, v162, v163
	v_cvt_pk_bf16_f32 v82, v164, v165
	v_cvt_pk_bf16_f32 v83, v166, v167
	v_cvt_pk_bf16_f32 v84, v168, v169
	v_cvt_pk_bf16_f32 v85, v170, v171
	v_cvt_pk_bf16_f32 v86, v172, v173
	v_cvt_pk_bf16_f32 v87, v174, v175
	v_cvt_pk_bf16_f32 v88, v176, v177
	v_cvt_pk_bf16_f32 v89, v178, v179
	v_add_f32_e32 v230, v204, v230
	ds_read_b64_tr_b16 v[148:149], v231 offset:27648
	ds_read_b64_tr_b16 v[150:151], v231 offset:30208
	ds_read_b64_tr_b16 v[152:153], v231 offset:32768
	ds_read_b64_tr_b16 v[154:155], v231 offset:35328
	ds_read_b64_tr_b16 v[156:157], v231 offset:32832
	ds_read_b64_tr_b16 v[158:159], v231 offset:35392
	s_setprio 1
	s_waitcnt lgkmcnt(14)
	v_mfma_f32_32x32x16_bf16 v[34:49], v[90:93], v[98:101], v[34:49]
	ds_read_b64_tr_b16 v[160:161], v231 offset:17536
	ds_read_b64_tr_b16 v[162:163], v231 offset:20096
	s_waitcnt lgkmcnt(14)
	v_mfma_f32_32x32x16_bf16 v[50:65], v[94:97], v[98:101], v[50:65]
	ds_read_b64_tr_b16 v[164:165], v231 offset:17600
	ds_read_b64_tr_b16 v[166:167], v231 offset:20160
	s_waitcnt lgkmcnt(14)
	v_mfma_f32_32x32x16_bf16 v[34:49], v[106:109], v[102:105], v[34:49]
	ds_read_b64_tr_b16 v[168:169], v231 offset:22656
	ds_read_b64_tr_b16 v[170:171], v231 offset:25216
	s_waitcnt lgkmcnt(14)
	v_mfma_f32_32x32x16_bf16 v[50:65], v[110:113], v[102:105], v[50:65]
	ds_read_b64_tr_b16 v[172:173], v231 offset:22720
	ds_read_b64_tr_b16 v[174:175], v231 offset:25280
	s_waitcnt lgkmcnt(14)
	v_mfma_f32_32x32x16_bf16 v[34:49], v[240:243], v[82:85], v[34:49]
	ds_read_b64_tr_b16 v[176:177], v231 offset:27776
	ds_read_b64_tr_b16 v[178:179], v231 offset:30336
	s_waitcnt lgkmcnt(14)
	v_mfma_f32_32x32x16_bf16 v[50:65], v[148:151], v[82:85], v[50:65]
	ds_read_b64_tr_b16 v[90:91], v231 offset:27840
	ds_read_b64_tr_b16 v[92:93], v231 offset:30400
	s_waitcnt lgkmcnt(14)
	v_mfma_f32_32x32x16_bf16 v[50:65], v[152:155], v[86:89], v[50:65]
	ds_read_b64_tr_b16 v[94:95], v231 offset:32896
	ds_read_b64_tr_b16 v[96:97], v231 offset:35456
	s_waitcnt lgkmcnt(14)
	v_mfma_f32_32x32x16_bf16 v[34:49], v[156:159], v[86:89], v[34:49]
	ds_read_b64_tr_b16 v[106:107], v231 offset:32960
	ds_read_b64_tr_b16 v[108:109], v231 offset:35520
	s_waitcnt vmcnt(0)
	ds_write_b128 v226, v[132:135]
	ds_write_b128 v228, v[140:143]
	ds_write_b128 v227, v[136:139] offset:55552
	ds_write_b128 v229, v[144:147] offset:55552
	global_load_dwordx4 v[136:139], v[196:197], off offset:2048
	global_load_dwordx4 v[144:147], v[198:199], off offset:2048
	v_lshl_add_u64 v[196:197], v[196:197], 0, s[26:27]
	v_lshl_add_u64 v[198:199], v[198:199], 0, s[26:27]
	global_load_dwordx4 v[132:135], v[196:197], off offset:1024
	global_load_dwordx4 v[140:143], v[198:199], off offset:1024
	s_waitcnt lgkmcnt(15)
	v_mfma_f32_32x32x16_bf16 v[18:33], v[160:163], v[98:101], v[18:33]
	ds_read_b128 v[240:243], v234 offset:38144
	s_waitcnt lgkmcnt(15)
	v_mfma_f32_32x32x16_bf16 v[2:17], v[164:167], v[98:101], v[2:17]
	ds_read_b128 v[148:151], v234 offset:46848
	s_waitcnt lgkmcnt(15)
	v_mfma_f32_32x32x16_bf16 v[18:33], v[168:171], v[102:105], v[18:33]
	ds_read_b128 v[152:155], v234 offset:38176
	s_waitcnt lgkmcnt(15)
	v_mfma_f32_32x32x16_bf16 v[2:17], v[172:175], v[102:105], v[2:17]
	ds_read_b128 v[156:159], v234 offset:46880
	s_waitcnt lgkmcnt(14)
	v_mfma_f32_32x32x16_bf16 v[18:33], v[176:179], v[82:85], v[18:33]
	ds_read_b128 v[160:163], v234 offset:38208
	s_waitcnt lgkmcnt(13)
	v_mfma_f32_32x32x16_bf16 v[2:17], v[90:93], v[82:85], v[2:17]
	ds_read_b128 v[164:167], v234 offset:46912
	s_waitcnt lgkmcnt(12)
	v_mfma_f32_32x32x16_bf16 v[18:33], v[94:97], v[86:89], v[18:33]
	ds_read_b128 v[168:171], v234 offset:38240
	s_waitcnt lgkmcnt(11)
	v_mfma_f32_32x32x16_bf16 v[2:17], v[106:109], v[86:89], v[2:17]
	ds_read_b128 v[172:175], v234 offset:46944
	s_waitcnt lgkmcnt(7)
	v_mfma_f32_32x32x16_bf16 v[98:113], v[240:243], v[116:119], v[66:81]
	s_waitcnt lgkmcnt(6)
	v_mfma_f32_32x32x16_bf16 v[82:97], v[148:151], v[116:119], v[66:81]
	s_waitcnt lgkmcnt(5)
	v_mfma_f32_32x32x16_bf16 v[98:113], v[152:155], v[120:123], v[98:113]
	s_waitcnt lgkmcnt(4)
	v_mfma_f32_32x32x16_bf16 v[82:97], v[156:159], v[120:123], v[82:97]
	s_waitcnt lgkmcnt(3)
	v_mfma_f32_32x32x16_bf16 v[98:113], v[160:163], v[124:127], v[98:113]
	s_waitcnt lgkmcnt(2)
	v_mfma_f32_32x32x16_bf16 v[82:97], v[164:167], v[124:127], v[82:97]
	s_waitcnt lgkmcnt(1)
	v_mfma_f32_32x32x16_bf16 v[98:113], v[168:171], v[128:131], v[98:113]
	s_waitcnt lgkmcnt(0)
	v_mfma_f32_32x32x16_bf16 v[82:97], v[172:175], v[128:131], v[82:97]
	s_setprio 0
	s_waitcnt lgkmcnt(0)
	s_barrier
	s_add_i32 s75, s75, 1
	s_add_i32 s74, s74, 64
	s_cmp_le_i32 s75, s23
	s_cbranch_scc1 .Ldb_s_even
